# attention work queue: ticket atomic issued at the start of the unit epilogue (latency hidden under gate loads/stores)
# speedup vs baseline: 1.0128x; 1.0069x over previous
.LBB0_628:
	s_or_b64 exec, exec, s[4:5]
	v_readlane_b32 s4, v254, 53
	v_readlane_b32 s5, v254, 54
	s_lshl_b32 s96, s4, 6
	s_lshl_b64 s[4:5], s[96:97], 2
	v_readlane_b32 s3, v253, 56
	s_add_u32 s8, s3, s4
	v_readlane_b32 s3, v253, 57
	s_addc_u32 s9, s3, s5
	s_waitcnt lgkmcnt(0)
	s_barrier
	s_cmp_lg_u32 s33, 0
	s_cbranch_scc1 .Lq_pf0
	s_mov_b64 s[10:11], exec
	s_mov_b64 exec, 1
	v_mov_b32_e32 v176, 1
	global_atomic_add v176, v13, v176, s[8:9] sc0
	s_mov_b64 exec, s[10:11]
.Lq_pf0:
	s_branch .LBB0_632

.LBB0_630:
	v_readlane_b32 s4, v253, 38
	v_lshlrev_b64 v[0:1], 1, v[134:135]
	v_readlane_b32 s5, v253, 39
	v_pk_mul_f32 v[10:11], v[16:17], v[2:3] op_sel_hi:[1,0]
	v_pk_mul_f32 v[14:15], v[14:15], v[2:3] op_sel_hi:[1,0]
	v_lshl_add_u64 v[4:5], s[4:5], 0, v[0:1]
	global_load_dwordx2 v[190:191], v[4:5], off
	global_load_dwordx2 v[192:193], v[4:5], off offset:64
	global_load_dwordx2 v[194:195], v[4:5], off offset:16
	global_load_dwordx2 v[196:197], v[4:5], off offset:80
	global_load_dwordx2 v[198:199], v[4:5], off offset:32
	global_load_dwordx2 v[200:201], v[4:5], off offset:96
	global_load_dwordx2 v[202:203], v[4:5], off offset:48
	global_load_dwordx2 v[204:205], v[4:5], off offset:112
	s_cmp_lg_u32 s33, 0
	s_cbranch_scc1 .Lq_pf1
	s_mov_b64 s[10:11], exec
	s_mov_b64 exec, 1
	v_mov_b32_e32 v176, 1
	global_atomic_add v176, v13, v176, s[8:9] sc0
	s_mov_b64 exec, s[10:11]
.Lq_pf1:
	v_pk_mul_f32 v[16:17], v[32:33], v[2:3] op_sel_hi:[1,0]
	v_pk_mul_f32 v[30:31], v[30:31], v[2:3] op_sel_hi:[1,0]
	v_lshl_add_u64 v[0:1], s[70:71], 0, v[0:1]
	s_mov_b64 s[4:5], 0
	s_waitcnt vmcnt(7)
	v_mov_b32_e32 v6, v190
	v_mov_b32_e32 v7, v191
	v_lshlrev_b32_e32 v32, 16, v6
	v_and_b32_e32 v33, 0xffff0000, v6
	v_lshlrev_b32_e32 v6, 16, v7
	v_and_b32_e32 v7, 0xffff0000, v7
	v_pk_mul_f32 v[6:7], v[10:11], v[6:7]
	v_pk_mul_f32 v[10:11], v[14:15], v[32:33]
	s_waitcnt vmcnt(6)
	v_mov_b32_e32 v8, v192
	v_mov_b32_e32 v9, v193
	v_lshlrev_b32_e32 v14, 16, v8
	v_and_b32_e32 v15, 0xffff0000, v8
	v_lshlrev_b32_e32 v8, 16, v9
	v_and_b32_e32 v9, 0xffff0000, v9
	v_pk_mul_f32 v[8:9], v[16:17], v[8:9]
	v_pk_mul_f32 v[14:15], v[30:31], v[14:15]
	v_cvt_pk_bf16_f32 v10, v10, v11
	v_cvt_pk_bf16_f32 v11, v6, v7
	v_cvt_pk_bf16_f32 v6, v14, v15
	v_cvt_pk_bf16_f32 v7, v8, v9
	global_store_dwordx2 v[0:1], v[10:11], off
	global_store_dwordx2 v[0:1], v[6:7], off offset:64
	v_pk_mul_f32 v[14:15], v[20:21], v[2:3] op_sel_hi:[1,0]
	v_pk_mul_f32 v[10:11], v[18:19], v[2:3] op_sel_hi:[1,0]
	v_pk_mul_f32 v[16:17], v[34:35], v[2:3] op_sel_hi:[1,0]
	v_pk_mul_f32 v[18:19], v[36:37], v[2:3] op_sel_hi:[1,0]
	s_waitcnt vmcnt(7)
	v_mov_b32_e32 v6, v194
	v_mov_b32_e32 v7, v195
	v_lshlrev_b32_e32 v20, 16, v6
	v_and_b32_e32 v21, 0xffff0000, v6
	v_lshlrev_b32_e32 v6, 16, v7
	v_and_b32_e32 v7, 0xffff0000, v7
	v_pk_mul_f32 v[6:7], v[14:15], v[6:7]
	s_waitcnt vmcnt(6)
	v_mov_b32_e32 v8, v196
	v_mov_b32_e32 v9, v197
	v_lshlrev_b32_e32 v14, 16, v8
	v_and_b32_e32 v15, 0xffff0000, v8
	v_lshlrev_b32_e32 v8, 16, v9
	v_and_b32_e32 v9, 0xffff0000, v9
	v_pk_mul_f32 v[10:11], v[10:11], v[20:21]
	v_pk_mul_f32 v[8:9], v[18:19], v[8:9]
	v_pk_mul_f32 v[14:15], v[16:17], v[14:15]
	v_cvt_pk_bf16_f32 v10, v10, v11
	v_cvt_pk_bf16_f32 v11, v6, v7
	v_cvt_pk_bf16_f32 v6, v14, v15
	v_cvt_pk_bf16_f32 v7, v8, v9
	global_store_dwordx2 v[0:1], v[10:11], off offset:16
	global_store_dwordx2 v[0:1], v[6:7], off offset:80
	v_pk_mul_f32 v[14:15], v[24:25], v[2:3] op_sel_hi:[1,0]
	v_pk_mul_f32 v[10:11], v[22:23], v[2:3] op_sel_hi:[1,0]
	v_pk_mul_f32 v[16:17], v[38:39], v[2:3] op_sel_hi:[1,0]
	v_pk_mul_f32 v[18:19], v[40:41], v[2:3] op_sel_hi:[1,0]
	s_waitcnt vmcnt(7)
	v_mov_b32_e32 v6, v198
	v_mov_b32_e32 v7, v199
	v_lshlrev_b32_e32 v20, 16, v6
	v_and_b32_e32 v21, 0xffff0000, v6
	v_lshlrev_b32_e32 v6, 16, v7
	v_and_b32_e32 v7, 0xffff0000, v7
	v_pk_mul_f32 v[6:7], v[14:15], v[6:7]
	s_waitcnt vmcnt(6)
	v_mov_b32_e32 v8, v200
	v_mov_b32_e32 v9, v201
	v_lshlrev_b32_e32 v14, 16, v8
	v_and_b32_e32 v15, 0xffff0000, v8
	v_lshlrev_b32_e32 v8, 16, v9
	v_and_b32_e32 v9, 0xffff0000, v9
	v_pk_mul_f32 v[10:11], v[10:11], v[20:21]
	v_pk_mul_f32 v[8:9], v[18:19], v[8:9]
	v_pk_mul_f32 v[14:15], v[16:17], v[14:15]
	v_cvt_pk_bf16_f32 v10, v10, v11
	v_cvt_pk_bf16_f32 v11, v6, v7
	v_cvt_pk_bf16_f32 v6, v14, v15
	v_cvt_pk_bf16_f32 v7, v8, v9
	global_store_dwordx2 v[0:1], v[10:11], off offset:32
	global_store_dwordx2 v[0:1], v[6:7], off offset:96
	v_pk_mul_f32 v[10:11], v[28:29], v[2:3] op_sel_hi:[1,0]
	v_pk_mul_f32 v[8:9], v[26:27], v[2:3] op_sel_hi:[1,0]
	v_pk_mul_f32 v[14:15], v[42:43], v[2:3] op_sel_hi:[1,0]
	v_pk_mul_f32 v[2:3], v[44:45], v[2:3] op_sel_hi:[1,0]
	s_waitcnt vmcnt(7)
	v_mov_b32_e32 v6, v202
	v_mov_b32_e32 v7, v203
	v_lshlrev_b32_e32 v16, 16, v6
	v_and_b32_e32 v17, 0xffff0000, v6
	v_lshlrev_b32_e32 v6, 16, v7
	v_and_b32_e32 v7, 0xffff0000, v7
	v_pk_mul_f32 v[6:7], v[10:11], v[6:7]
	s_waitcnt vmcnt(6)
	v_mov_b32_e32 v4, v204
	v_mov_b32_e32 v5, v205
	v_lshlrev_b32_e32 v10, 16, v4
	v_and_b32_e32 v11, 0xffff0000, v4
	v_lshlrev_b32_e32 v4, 16, v5
	v_and_b32_e32 v5, 0xffff0000, v5
	v_pk_mul_f32 v[8:9], v[8:9], v[16:17]
	v_pk_mul_f32 v[2:3], v[2:3], v[4:5]
	v_pk_mul_f32 v[4:5], v[14:15], v[10:11]
	v_cvt_pk_bf16_f32 v8, v8, v9
	v_cvt_pk_bf16_f32 v9, v6, v7
	v_cvt_pk_bf16_f32 v4, v4, v5
	v_cvt_pk_bf16_f32 v5, v2, v3
	global_store_dwordx2 v[0:1], v[8:9], off offset:48
	global_store_dwordx2 v[0:1], v[4:5], off offset:112

.LBB0_632:
	v_mbcnt_lo_u32_b32 v0, -1, 0
	v_mbcnt_hi_u32_b32 v0, -1, v0
	s_mov_b32 s3, s33
	s_nop 0
	v_lshl_or_b32 v0, s3, 6, v0
	v_cmp_eq_u32_e32 vcc, 0, v0
	s_barrier
	s_and_saveexec_b64 s[4:5], vcc
	s_cbranch_execz .LBB0_636
	s_waitcnt vmcnt(0)
	v_mov_b32_e32 v1, s2
	ds_write_b32 v1, v176
